# scan phase inner 16-step body hand-scheduled (software pipelined, DPP hazards filled) + grid sync counter in device memory
# speedup vs baseline: 1.0805x; 1.0805x over previous
; DI void phase_scan(const Params& P, int l, char* smem) {
;     ...
;       {
;         float4 Ar[4], Aw[4], Ak[4], Aa[4], Ab[4], Br[4], Bw[4], Bk[4], Ba[4], Bb[4];
;         float Av[4], Bv[4];
;         SCAN_LOAD(A, 0);
;         SCAN_LOAD(B, 1);
;         SCAN_STEPS(A, 0);
;         SCAN_LOAD(A, 2);
;         SCAN_STEPS(B, 1);
;         SCAN_LOAD(B, 3);
;         SCAN_STEPS(A, 2);
;         SCAN_STEPS(B, 3);
;       }
.LBB0_513:
	s_add_i32 s8, s20, 1
	s_bitcmp1_b32 s20, 0
	s_cselect_b32 s9, 0x6000, 0
	v_lshl_or_b32 v219, v172, 2, s9
	s_lshl_b32 s10, s19, 2
	s_or_b32 s9, s9, s10
	v_lshl_add_u32 v218, v170, 2, s9
	ds_read_b128 v[40:43], v219 offset:512
	ds_read_b32 v60, v218 offset:1280
	ds_read_b128 v[44:47], v219 offset:768
	ds_read_b128 v[48:51], v219 offset:256
	ds_read_b128 v[52:55], v219 offset:1024
	ds_read_b128 v[56:59], v219
	ds_read_b128 v[64:67], v219 offset:2048
	ds_read_b32 v84, v218 offset:2816
	ds_read_b128 v[68:71], v219 offset:2304
	ds_read_b128 v[72:75], v219 offset:1792
	ds_read_b128 v[76:79], v219 offset:2560
	ds_read_b128 v[80:83], v219 offset:1536
	s_cmp_lt_u32 s20, 16
	s_movk_i32 s9, 0x41ff
	s_cselect_b32 s9, 0xff, s9
	s_andn2_b64 vcc, exec, s[16:17]
	s_mov_b32 s10, 0x10001
	s_mov_b32 s11, 0x10001
	s_waitcnt lgkmcnt(10)
	v_mul_f32_e32 v156, v60, v40
	v_mul_f32_e32 v157, v60, v41
	v_mul_f32_e32 v158, v60, v42
	v_mul_f32_e32 v159, v60, v43
	s_waitcnt lgkmcnt(9)
	ds_read_b128 v[88:91], v219 offset:3584
	ds_read_b32 v108, v218 offset:4352
	ds_read_b128 v[92:95], v219 offset:3840
	ds_read_b128 v[96:99], v219 offset:3328
	ds_read_b128 v[100:103], v219 offset:4096
	ds_read_b128 v[104:107], v219 offset:3072
	v_mul_f32_e32 v164, v126, v44
	v_fma_f32 v164, v127, v45, v164
	v_fma_f32 v164, v128, v46, v164
	v_fma_f32 v164, v129, v47, v164
	s_waitcnt lgkmcnt(14)
	v_fma_f32 v156, v126, v48, v156
	s_nop 0
	v_add_f32_dpp v164, v164, v164 quad_perm:[1,0,3,2] row_mask:0xf bank_mask:0xf bound_ctrl:1
	v_fma_f32 v157, v127, v49, v157
	s_nop 0
	v_add_f32_dpp v164, v164, v164 quad_perm:[2,3,0,1] row_mask:0xf bank_mask:0xf bound_ctrl:1
	v_fma_f32 v158, v128, v50, v158
	s_nop 0
	v_add_f32_dpp v164, v164, v164 row_half_mirror row_mask:0xf bank_mask:0xf bound_ctrl:1
	v_fma_f32 v159, v129, v51, v159
	s_nop 0
	v_add_f32_dpp v164, v164, v164 row_mirror row_mask:0xf bank_mask:0xf bound_ctrl:1
	s_waitcnt lgkmcnt(10)
	v_mul_f32_e32 v160, v84, v64
	s_nop 0
	v_fma_f32 v126, v164, v52, v156
	v_fma_f32 v127, v164, v53, v157
	v_mul_f32_e32 v161, v84, v65
	v_fma_f32 v128, v164, v54, v158
	v_mul_f32_e32 v162, v84, v66
	v_fma_f32 v129, v164, v55, v159
	v_mul_f32_e32 v163, v84, v67
	s_waitcnt lgkmcnt(9)
	ds_read_b128 v[132:135], v219 offset:5120
	ds_read_b32 v152, v218 offset:5888
	ds_read_b128 v[136:139], v219 offset:5376
	ds_read_b128 v[140:143], v219 offset:4864
	ds_read_b128 v[144:147], v219 offset:5632
	ds_read_b128 v[148:151], v219 offset:4608
	v_mul_f32_e32 v164, v126, v68
	v_mul_f32_e32 v165, v126, v56
	v_fma_f32 v164, v127, v69, v164
	v_fma_f32 v165, v127, v57, v165
	v_fma_f32 v164, v128, v70, v164
	v_fma_f32 v165, v128, v58, v165
	v_fma_f32 v164, v129, v71, v164
	v_fma_f32 v165, v129, v59, v165
	s_waitcnt lgkmcnt(14)
	v_fma_f32 v160, v126, v72, v160
	v_add_f32_dpp v164, v164, v164 quad_perm:[1,0,3,2] row_mask:0xf bank_mask:0xf bound_ctrl:1
	v_fma_f32 v161, v127, v73, v161
	v_add_f32_dpp v165, v165, v165 quad_perm:[1,0,3,2] row_mask:0xf bank_mask:0xf bound_ctrl:1
	v_add_f32_dpp v164, v164, v164 quad_perm:[2,3,0,1] row_mask:0xf bank_mask:0xf bound_ctrl:1
	v_fma_f32 v162, v128, v74, v162
	v_add_f32_dpp v165, v165, v165 quad_perm:[2,3,0,1] row_mask:0xf bank_mask:0xf bound_ctrl:1
	v_add_f32_dpp v164, v164, v164 row_half_mirror row_mask:0xf bank_mask:0xf bound_ctrl:1
	v_fma_f32 v163, v129, v75, v163
	v_add_f32_dpp v165, v165, v165 row_half_mirror row_mask:0xf bank_mask:0xf bound_ctrl:1
	v_add_f32_dpp v164, v164, v164 row_mirror row_mask:0xf bank_mask:0xf bound_ctrl:1
	s_waitcnt lgkmcnt(10)
	v_mul_f32_e32 v156, v108, v88
	v_add_f32_dpp v165, v165, v165 row_mirror row_mask:0xf bank_mask:0xf bound_ctrl:1
	v_fma_f32 v126, v164, v76, v160
	v_cndmask_b32_e64 v11, v1, v165, s[10:11]
	s_lshl_b64 s[10:11], s[10:11], 1
	v_fma_f32 v127, v164, v77, v161
	v_mul_f32_e32 v157, v108, v89
	v_fma_f32 v128, v164, v78, v162
	v_mul_f32_e32 v158, v108, v90
	v_fma_f32 v129, v164, v79, v163
	v_mul_f32_e32 v159, v108, v91
	s_waitcnt lgkmcnt(9)
	ds_read_b128 v[40:43], v219 offset:6656
	ds_read_b32 v60, v218 offset:7424
	ds_read_b128 v[44:47], v219 offset:6912
	ds_read_b128 v[48:51], v219 offset:6400
	ds_read_b128 v[52:55], v219 offset:7168
	ds_read_b128 v[56:59], v219 offset:6144
	v_mul_f32_e32 v164, v126, v92
	v_mul_f32_e32 v165, v126, v80
	v_fma_f32 v164, v127, v93, v164
	v_fma_f32 v165, v127, v81, v165
	v_fma_f32 v164, v128, v94, v164
	v_fma_f32 v165, v128, v82, v165
	v_fma_f32 v164, v129, v95, v164
	v_fma_f32 v165, v129, v83, v165
	s_waitcnt lgkmcnt(14)
	v_fma_f32 v156, v126, v96, v156
	v_add_f32_dpp v164, v164, v164 quad_perm:[1,0,3,2] row_mask:0xf bank_mask:0xf bound_ctrl:1
	v_fma_f32 v157, v127, v97, v157
	v_add_f32_dpp v165, v165, v165 quad_perm:[1,0,3,2] row_mask:0xf bank_mask:0xf bound_ctrl:1
	v_add_f32_dpp v164, v164, v164 quad_perm:[2,3,0,1] row_mask:0xf bank_mask:0xf bound_ctrl:1
	v_fma_f32 v158, v128, v98, v158
	v_add_f32_dpp v165, v165, v165 quad_perm:[2,3,0,1] row_mask:0xf bank_mask:0xf bound_ctrl:1
	v_add_f32_dpp v164, v164, v164 row_half_mirror row_mask:0xf bank_mask:0xf bound_ctrl:1
	v_fma_f32 v159, v129, v99, v159
	v_add_f32_dpp v165, v165, v165 row_half_mirror row_mask:0xf bank_mask:0xf bound_ctrl:1
	v_add_f32_dpp v164, v164, v164 row_mirror row_mask:0xf bank_mask:0xf bound_ctrl:1
	s_waitcnt lgkmcnt(10)
	v_mul_f32_e32 v160, v152, v132
	v_add_f32_dpp v165, v165, v165 row_mirror row_mask:0xf bank_mask:0xf bound_ctrl:1
	v_fma_f32 v126, v164, v100, v156
	v_cndmask_b32_e64 v11, v11, v165, s[10:11]
	s_lshl_b64 s[10:11], s[10:11], 1
	v_fma_f32 v127, v164, v101, v157
	v_mul_f32_e32 v161, v152, v133
	v_fma_f32 v128, v164, v102, v158
	v_mul_f32_e32 v162, v152, v134
	v_fma_f32 v129, v164, v103, v159
	v_mul_f32_e32 v163, v152, v135
	s_waitcnt lgkmcnt(9)
; DI void phase_scan(const Params& P, int l, char* smem) {
;     ...
;       {
;         float4 Ar[4], Aw[4], Ak[4], Aa[4], Ab[4], Br[4], Bw[4], Bk[4], Ba[4], Bb[4];
;         float Av[4], Bv[4];
;         SCAN_LOAD(A, 0);
;         SCAN_LOAD(B, 1);
;         SCAN_STEPS(A, 0);
;         SCAN_LOAD(A, 2);
;         SCAN_STEPS(B, 1);
;         SCAN_LOAD(B, 3);
;         SCAN_STEPS(A, 2);
;         SCAN_STEPS(B, 3);
	ds_read_b128 v[64:67], v219 offset:8192
	ds_read_b32 v84, v218 offset:8960
	ds_read_b128 v[68:71], v219 offset:8448
	ds_read_b128 v[72:75], v219 offset:7936
	ds_read_b128 v[76:79], v219 offset:8704
	ds_read_b128 v[80:83], v219 offset:7680
	v_mul_f32_e32 v164, v126, v136
	v_mul_f32_e32 v165, v126, v104
	v_fma_f32 v164, v127, v137, v164
	v_fma_f32 v165, v127, v105, v165
	v_fma_f32 v164, v128, v138, v164
	v_fma_f32 v165, v128, v106, v165
	v_fma_f32 v164, v129, v139, v164
	v_fma_f32 v165, v129, v107, v165
	s_waitcnt lgkmcnt(14)
	v_fma_f32 v160, v126, v140, v160
	v_add_f32_dpp v164, v164, v164 quad_perm:[1,0,3,2] row_mask:0xf bank_mask:0xf bound_ctrl:1
	v_fma_f32 v161, v127, v141, v161
	v_add_f32_dpp v165, v165, v165 quad_perm:[1,0,3,2] row_mask:0xf bank_mask:0xf bound_ctrl:1
	v_add_f32_dpp v164, v164, v164 quad_perm:[2,3,0,1] row_mask:0xf bank_mask:0xf bound_ctrl:1
	v_fma_f32 v162, v128, v142, v162
	v_add_f32_dpp v165, v165, v165 quad_perm:[2,3,0,1] row_mask:0xf bank_mask:0xf bound_ctrl:1
	v_add_f32_dpp v164, v164, v164 row_half_mirror row_mask:0xf bank_mask:0xf bound_ctrl:1
	v_fma_f32 v163, v129, v143, v163
	v_add_f32_dpp v165, v165, v165 row_half_mirror row_mask:0xf bank_mask:0xf bound_ctrl:1
	v_add_f32_dpp v164, v164, v164 row_mirror row_mask:0xf bank_mask:0xf bound_ctrl:1
	s_waitcnt lgkmcnt(10)
	v_mul_f32_e32 v156, v60, v40
	v_add_f32_dpp v165, v165, v165 row_mirror row_mask:0xf bank_mask:0xf bound_ctrl:1
	v_fma_f32 v126, v164, v144, v160
	v_cndmask_b32_e64 v11, v11, v165, s[10:11]
	s_lshl_b64 s[10:11], s[10:11], 1
	v_fma_f32 v127, v164, v145, v161
	v_mul_f32_e32 v157, v60, v41
	v_fma_f32 v128, v164, v146, v162
	v_mul_f32_e32 v158, v60, v42
	v_fma_f32 v129, v164, v147, v163
	v_mul_f32_e32 v159, v60, v43
	s_waitcnt lgkmcnt(9)
	ds_read_b128 v[88:91], v219 offset:9728
	ds_read_b32 v108, v218 offset:10496
	ds_read_b128 v[92:95], v219 offset:9984
	ds_read_b128 v[96:99], v219 offset:9472
	ds_read_b128 v[100:103], v219 offset:10240
	ds_read_b128 v[104:107], v219 offset:9216
	v_mul_f32_e32 v164, v126, v44
	v_mul_f32_e32 v165, v126, v148
	v_fma_f32 v164, v127, v45, v164
	v_fma_f32 v165, v127, v149, v165
	v_fma_f32 v164, v128, v46, v164
	v_fma_f32 v165, v128, v150, v165
	v_fma_f32 v164, v129, v47, v164
	v_fma_f32 v165, v129, v151, v165
	s_waitcnt lgkmcnt(14)
	v_fma_f32 v156, v126, v48, v156
	v_add_f32_dpp v164, v164, v164 quad_perm:[1,0,3,2] row_mask:0xf bank_mask:0xf bound_ctrl:1
	v_fma_f32 v157, v127, v49, v157
	v_add_f32_dpp v165, v165, v165 quad_perm:[1,0,3,2] row_mask:0xf bank_mask:0xf bound_ctrl:1
	v_add_f32_dpp v164, v164, v164 quad_perm:[2,3,0,1] row_mask:0xf bank_mask:0xf bound_ctrl:1
	v_fma_f32 v158, v128, v50, v158
	v_add_f32_dpp v165, v165, v165 quad_perm:[2,3,0,1] row_mask:0xf bank_mask:0xf bound_ctrl:1
	v_add_f32_dpp v164, v164, v164 row_half_mirror row_mask:0xf bank_mask:0xf bound_ctrl:1
	v_fma_f32 v159, v129, v51, v159
	v_add_f32_dpp v165, v165, v165 row_half_mirror row_mask:0xf bank_mask:0xf bound_ctrl:1
	v_add_f32_dpp v164, v164, v164 row_mirror row_mask:0xf bank_mask:0xf bound_ctrl:1
	s_waitcnt lgkmcnt(10)
	v_mul_f32_e32 v160, v84, v64
	v_add_f32_dpp v165, v165, v165 row_mirror row_mask:0xf bank_mask:0xf bound_ctrl:1
	v_fma_f32 v126, v164, v52, v156
	v_cndmask_b32_e64 v11, v11, v165, s[10:11]
	s_lshl_b64 s[10:11], s[10:11], 1
	v_fma_f32 v127, v164, v53, v157
	v_mul_f32_e32 v161, v84, v65
	v_fma_f32 v128, v164, v54, v158
	v_mul_f32_e32 v162, v84, v66
	v_fma_f32 v129, v164, v55, v159
	v_mul_f32_e32 v163, v84, v67
	s_waitcnt lgkmcnt(9)
	ds_read_b128 v[132:135], v219 offset:11264
	ds_read_b32 v152, v218 offset:12032
	ds_read_b128 v[136:139], v219 offset:11520
	ds_read_b128 v[140:143], v219 offset:11008
	ds_read_b128 v[144:147], v219 offset:11776
	ds_read_b128 v[148:151], v219 offset:10752
	v_mul_f32_e32 v164, v126, v68
	v_mul_f32_e32 v165, v126, v56
	v_fma_f32 v164, v127, v69, v164
	v_fma_f32 v165, v127, v57, v165
	v_fma_f32 v164, v128, v70, v164
	v_fma_f32 v165, v128, v58, v165
	v_fma_f32 v164, v129, v71, v164
	v_fma_f32 v165, v129, v59, v165
	s_waitcnt lgkmcnt(14)
	v_fma_f32 v160, v126, v72, v160
	v_add_f32_dpp v164, v164, v164 quad_perm:[1,0,3,2] row_mask:0xf bank_mask:0xf bound_ctrl:1
	v_fma_f32 v161, v127, v73, v161
	v_add_f32_dpp v165, v165, v165 quad_perm:[1,0,3,2] row_mask:0xf bank_mask:0xf bound_ctrl:1
	v_add_f32_dpp v164, v164, v164 quad_perm:[2,3,0,1] row_mask:0xf bank_mask:0xf bound_ctrl:1
	v_fma_f32 v162, v128, v74, v162
	v_add_f32_dpp v165, v165, v165 quad_perm:[2,3,0,1] row_mask:0xf bank_mask:0xf bound_ctrl:1
	v_add_f32_dpp v164, v164, v164 row_half_mirror row_mask:0xf bank_mask:0xf bound_ctrl:1
	v_fma_f32 v163, v129, v75, v163
	v_add_f32_dpp v165, v165, v165 row_half_mirror row_mask:0xf bank_mask:0xf bound_ctrl:1
	v_add_f32_dpp v164, v164, v164 row_mirror row_mask:0xf bank_mask:0xf bound_ctrl:1
	s_waitcnt lgkmcnt(10)
	v_mul_f32_e32 v156, v108, v88
	v_add_f32_dpp v165, v165, v165 row_mirror row_mask:0xf bank_mask:0xf bound_ctrl:1
	v_fma_f32 v126, v164, v76, v160
	v_cndmask_b32_e64 v11, v11, v165, s[10:11]
	s_lshl_b64 s[10:11], s[10:11], 1
	v_fma_f32 v127, v164, v77, v161
	v_mul_f32_e32 v157, v108, v89
	v_fma_f32 v128, v164, v78, v162
	v_mul_f32_e32 v158, v108, v90
	v_fma_f32 v129, v164, v79, v163
	v_mul_f32_e32 v159, v108, v91
	s_waitcnt lgkmcnt(9)
	ds_read_b128 v[40:43], v219 offset:12800
	ds_read_b32 v60, v218 offset:13568
	ds_read_b128 v[44:47], v219 offset:13056
	ds_read_b128 v[48:51], v219 offset:12544
	ds_read_b128 v[52:55], v219 offset:13312
	ds_read_b128 v[56:59], v219 offset:12288
	v_mul_f32_e32 v164, v126, v92
	v_mul_f32_e32 v165, v126, v80
	v_fma_f32 v164, v127, v93, v164
	v_fma_f32 v165, v127, v81, v165
	v_fma_f32 v164, v128, v94, v164
	v_fma_f32 v165, v128, v82, v165
	v_fma_f32 v164, v129, v95, v164
	v_fma_f32 v165, v129, v83, v165
	s_waitcnt lgkmcnt(14)
; DI void phase_scan(const Params& P, int l, char* smem) {
;     ...
;       {
;         float4 Ar[4], Aw[4], Ak[4], Aa[4], Ab[4], Br[4], Bw[4], Bk[4], Ba[4], Bb[4];
;         float Av[4], Bv[4];
;         SCAN_LOAD(A, 0);
;         SCAN_LOAD(B, 1);
;         SCAN_STEPS(A, 0);
;         SCAN_LOAD(A, 2);
;         SCAN_STEPS(B, 1);
;         SCAN_LOAD(B, 3);
;         SCAN_STEPS(A, 2);
;         SCAN_STEPS(B, 3);
	v_fma_f32 v156, v126, v96, v156
	v_add_f32_dpp v164, v164, v164 quad_perm:[1,0,3,2] row_mask:0xf bank_mask:0xf bound_ctrl:1
	v_fma_f32 v157, v127, v97, v157
	v_add_f32_dpp v165, v165, v165 quad_perm:[1,0,3,2] row_mask:0xf bank_mask:0xf bound_ctrl:1
	v_add_f32_dpp v164, v164, v164 quad_perm:[2,3,0,1] row_mask:0xf bank_mask:0xf bound_ctrl:1
	v_fma_f32 v158, v128, v98, v158
	v_add_f32_dpp v165, v165, v165 quad_perm:[2,3,0,1] row_mask:0xf bank_mask:0xf bound_ctrl:1
	v_add_f32_dpp v164, v164, v164 row_half_mirror row_mask:0xf bank_mask:0xf bound_ctrl:1
	v_fma_f32 v159, v129, v99, v159
	v_add_f32_dpp v165, v165, v165 row_half_mirror row_mask:0xf bank_mask:0xf bound_ctrl:1
	v_add_f32_dpp v164, v164, v164 row_mirror row_mask:0xf bank_mask:0xf bound_ctrl:1
	s_waitcnt lgkmcnt(10)
	v_mul_f32_e32 v160, v152, v132
	v_add_f32_dpp v165, v165, v165 row_mirror row_mask:0xf bank_mask:0xf bound_ctrl:1
	v_fma_f32 v126, v164, v100, v156
	v_cndmask_b32_e64 v11, v11, v165, s[10:11]
	s_lshl_b64 s[10:11], s[10:11], 1
	v_fma_f32 v127, v164, v101, v157
	v_mul_f32_e32 v161, v152, v133
	v_fma_f32 v128, v164, v102, v158
	v_mul_f32_e32 v162, v152, v134
	v_fma_f32 v129, v164, v103, v159
	v_mul_f32_e32 v163, v152, v135
	s_waitcnt lgkmcnt(9)
	ds_read_b128 v[64:67], v219 offset:14336
	ds_read_b32 v84, v218 offset:15104
	ds_read_b128 v[68:71], v219 offset:14592
	ds_read_b128 v[72:75], v219 offset:14080
	ds_read_b128 v[76:79], v219 offset:14848
	ds_read_b128 v[80:83], v219 offset:13824
	v_mul_f32_e32 v164, v126, v136
	v_mul_f32_e32 v165, v126, v104
	v_fma_f32 v164, v127, v137, v164
	v_fma_f32 v165, v127, v105, v165
	v_fma_f32 v164, v128, v138, v164
	v_fma_f32 v165, v128, v106, v165
	v_fma_f32 v164, v129, v139, v164
	v_fma_f32 v165, v129, v107, v165
	s_waitcnt lgkmcnt(14)
	v_fma_f32 v160, v126, v140, v160
	v_add_f32_dpp v164, v164, v164 quad_perm:[1,0,3,2] row_mask:0xf bank_mask:0xf bound_ctrl:1
	v_fma_f32 v161, v127, v141, v161
	v_add_f32_dpp v165, v165, v165 quad_perm:[1,0,3,2] row_mask:0xf bank_mask:0xf bound_ctrl:1
	v_add_f32_dpp v164, v164, v164 quad_perm:[2,3,0,1] row_mask:0xf bank_mask:0xf bound_ctrl:1
	v_fma_f32 v162, v128, v142, v162
	v_add_f32_dpp v165, v165, v165 quad_perm:[2,3,0,1] row_mask:0xf bank_mask:0xf bound_ctrl:1
	v_add_f32_dpp v164, v164, v164 row_half_mirror row_mask:0xf bank_mask:0xf bound_ctrl:1
	v_fma_f32 v163, v129, v143, v163
	v_add_f32_dpp v165, v165, v165 row_half_mirror row_mask:0xf bank_mask:0xf bound_ctrl:1
	v_add_f32_dpp v164, v164, v164 row_mirror row_mask:0xf bank_mask:0xf bound_ctrl:1
	s_waitcnt lgkmcnt(10)
	v_mul_f32_e32 v156, v60, v40
	v_add_f32_dpp v165, v165, v165 row_mirror row_mask:0xf bank_mask:0xf bound_ctrl:1
	v_fma_f32 v126, v164, v144, v160
	v_cndmask_b32_e64 v11, v11, v165, s[10:11]
	s_lshl_b64 s[10:11], s[10:11], 1
	v_fma_f32 v127, v164, v145, v161
	v_mul_f32_e32 v157, v60, v41
	v_fma_f32 v128, v164, v146, v162
	v_mul_f32_e32 v158, v60, v42
	v_fma_f32 v129, v164, v147, v163
	v_mul_f32_e32 v159, v60, v43
	s_waitcnt lgkmcnt(9)
	ds_read_b128 v[88:91], v219 offset:15872
	ds_read_b32 v108, v218 offset:16640
	ds_read_b128 v[92:95], v219 offset:16128
	ds_read_b128 v[96:99], v219 offset:15616
	ds_read_b128 v[100:103], v219 offset:16384
	ds_read_b128 v[104:107], v219 offset:15360
	v_mul_f32_e32 v164, v126, v44
	v_mul_f32_e32 v165, v126, v148
	v_fma_f32 v164, v127, v45, v164
	v_fma_f32 v165, v127, v149, v165
	v_fma_f32 v164, v128, v46, v164
	v_fma_f32 v165, v128, v150, v165
	v_fma_f32 v164, v129, v47, v164
	v_fma_f32 v165, v129, v151, v165
	s_waitcnt lgkmcnt(14)
	v_fma_f32 v156, v126, v48, v156
	v_add_f32_dpp v164, v164, v164 quad_perm:[1,0,3,2] row_mask:0xf bank_mask:0xf bound_ctrl:1
	v_fma_f32 v157, v127, v49, v157
	v_add_f32_dpp v165, v165, v165 quad_perm:[1,0,3,2] row_mask:0xf bank_mask:0xf bound_ctrl:1
	v_add_f32_dpp v164, v164, v164 quad_perm:[2,3,0,1] row_mask:0xf bank_mask:0xf bound_ctrl:1
	v_fma_f32 v158, v128, v50, v158
	v_add_f32_dpp v165, v165, v165 quad_perm:[2,3,0,1] row_mask:0xf bank_mask:0xf bound_ctrl:1
	v_add_f32_dpp v164, v164, v164 row_half_mirror row_mask:0xf bank_mask:0xf bound_ctrl:1
	v_fma_f32 v159, v129, v51, v159
	v_add_f32_dpp v165, v165, v165 row_half_mirror row_mask:0xf bank_mask:0xf bound_ctrl:1
	v_add_f32_dpp v164, v164, v164 row_mirror row_mask:0xf bank_mask:0xf bound_ctrl:1
	s_waitcnt lgkmcnt(10)
	v_mul_f32_e32 v160, v84, v64
	v_add_f32_dpp v165, v165, v165 row_mirror row_mask:0xf bank_mask:0xf bound_ctrl:1
	v_fma_f32 v126, v164, v52, v156
	v_cndmask_b32_e64 v11, v11, v165, s[10:11]
	s_lshl_b64 s[10:11], s[10:11], 1
	v_fma_f32 v127, v164, v53, v157
	v_mul_f32_e32 v161, v84, v65
	v_fma_f32 v128, v164, v54, v158
	v_mul_f32_e32 v162, v84, v66
	v_fma_f32 v129, v164, v55, v159
	v_mul_f32_e32 v163, v84, v67
	s_waitcnt lgkmcnt(9)
	ds_read_b128 v[132:135], v219 offset:17408
	ds_read_b32 v152, v218 offset:18176
	ds_read_b128 v[136:139], v219 offset:17664
	ds_read_b128 v[140:143], v219 offset:17152
	ds_read_b128 v[144:147], v219 offset:17920
	ds_read_b128 v[148:151], v219 offset:16896
	v_mul_f32_e32 v164, v126, v68
	v_mul_f32_e32 v165, v126, v56
	v_fma_f32 v164, v127, v69, v164
	v_fma_f32 v165, v127, v57, v165
	v_fma_f32 v164, v128, v70, v164
	v_fma_f32 v165, v128, v58, v165
	v_fma_f32 v164, v129, v71, v164
	v_fma_f32 v165, v129, v59, v165
	s_waitcnt lgkmcnt(14)
; DI void phase_scan(const Params& P, int l, char* smem) {
;     ...
;       {
;         float4 Ar[4], Aw[4], Ak[4], Aa[4], Ab[4], Br[4], Bw[4], Bk[4], Ba[4], Bb[4];
;         float Av[4], Bv[4];
;         SCAN_LOAD(A, 0);
;         SCAN_LOAD(B, 1);
;         SCAN_STEPS(A, 0);
;         SCAN_LOAD(A, 2);
;         SCAN_STEPS(B, 1);
;         SCAN_LOAD(B, 3);
;         SCAN_STEPS(A, 2);
;         SCAN_STEPS(B, 3);
	v_fma_f32 v160, v126, v72, v160
	v_add_f32_dpp v164, v164, v164 quad_perm:[1,0,3,2] row_mask:0xf bank_mask:0xf bound_ctrl:1
	v_fma_f32 v161, v127, v73, v161
	v_add_f32_dpp v165, v165, v165 quad_perm:[1,0,3,2] row_mask:0xf bank_mask:0xf bound_ctrl:1
	v_add_f32_dpp v164, v164, v164 quad_perm:[2,3,0,1] row_mask:0xf bank_mask:0xf bound_ctrl:1
	v_fma_f32 v162, v128, v74, v162
	v_add_f32_dpp v165, v165, v165 quad_perm:[2,3,0,1] row_mask:0xf bank_mask:0xf bound_ctrl:1
	v_add_f32_dpp v164, v164, v164 row_half_mirror row_mask:0xf bank_mask:0xf bound_ctrl:1
	v_fma_f32 v163, v129, v75, v163
	v_add_f32_dpp v165, v165, v165 row_half_mirror row_mask:0xf bank_mask:0xf bound_ctrl:1
	v_add_f32_dpp v164, v164, v164 row_mirror row_mask:0xf bank_mask:0xf bound_ctrl:1
	s_waitcnt lgkmcnt(10)
	v_mul_f32_e32 v156, v108, v88
	v_add_f32_dpp v165, v165, v165 row_mirror row_mask:0xf bank_mask:0xf bound_ctrl:1
	v_fma_f32 v126, v164, v76, v160
	v_cndmask_b32_e64 v11, v11, v165, s[10:11]
	s_lshl_b64 s[10:11], s[10:11], 1
	v_fma_f32 v127, v164, v77, v161
	v_mul_f32_e32 v157, v108, v89
	v_fma_f32 v128, v164, v78, v162
	v_mul_f32_e32 v158, v108, v90
	v_fma_f32 v129, v164, v79, v163
	v_mul_f32_e32 v159, v108, v91
	s_waitcnt lgkmcnt(9)
	ds_read_b128 v[40:43], v219 offset:18944
	ds_read_b32 v60, v218 offset:19712
	ds_read_b128 v[44:47], v219 offset:19200
	ds_read_b128 v[48:51], v219 offset:18688
	ds_read_b128 v[52:55], v219 offset:19456
	ds_read_b128 v[56:59], v219 offset:18432
	v_mul_f32_e32 v164, v126, v92
	v_mul_f32_e32 v165, v126, v80
	v_fma_f32 v164, v127, v93, v164
	v_fma_f32 v165, v127, v81, v165
	v_fma_f32 v164, v128, v94, v164
	v_fma_f32 v165, v128, v82, v165
	v_fma_f32 v164, v129, v95, v164
	v_fma_f32 v165, v129, v83, v165
	s_waitcnt lgkmcnt(14)
	v_fma_f32 v156, v126, v96, v156
	v_add_f32_dpp v164, v164, v164 quad_perm:[1,0,3,2] row_mask:0xf bank_mask:0xf bound_ctrl:1
	v_fma_f32 v157, v127, v97, v157
	v_add_f32_dpp v165, v165, v165 quad_perm:[1,0,3,2] row_mask:0xf bank_mask:0xf bound_ctrl:1
	v_add_f32_dpp v164, v164, v164 quad_perm:[2,3,0,1] row_mask:0xf bank_mask:0xf bound_ctrl:1
	v_fma_f32 v158, v128, v98, v158
	v_add_f32_dpp v165, v165, v165 quad_perm:[2,3,0,1] row_mask:0xf bank_mask:0xf bound_ctrl:1
	v_add_f32_dpp v164, v164, v164 row_half_mirror row_mask:0xf bank_mask:0xf bound_ctrl:1
	v_fma_f32 v159, v129, v99, v159
	v_add_f32_dpp v165, v165, v165 row_half_mirror row_mask:0xf bank_mask:0xf bound_ctrl:1
	v_add_f32_dpp v164, v164, v164 row_mirror row_mask:0xf bank_mask:0xf bound_ctrl:1
	s_waitcnt lgkmcnt(10)
	v_mul_f32_e32 v160, v152, v132
	v_add_f32_dpp v165, v165, v165 row_mirror row_mask:0xf bank_mask:0xf bound_ctrl:1
	v_fma_f32 v126, v164, v100, v156
	v_cndmask_b32_e64 v11, v11, v165, s[10:11]
	s_lshl_b64 s[10:11], s[10:11], 1
	v_fma_f32 v127, v164, v101, v157
	v_mul_f32_e32 v161, v152, v133
	v_fma_f32 v128, v164, v102, v158
	v_mul_f32_e32 v162, v152, v134
	v_fma_f32 v129, v164, v103, v159
	v_mul_f32_e32 v163, v152, v135
	s_waitcnt lgkmcnt(9)
	ds_read_b128 v[64:67], v219 offset:20480
	ds_read_b32 v84, v218 offset:21248
	ds_read_b128 v[68:71], v219 offset:20736
	ds_read_b128 v[72:75], v219 offset:20224
	ds_read_b128 v[76:79], v219 offset:20992
	ds_read_b128 v[80:83], v219 offset:19968
	v_mul_f32_e32 v164, v126, v136
	v_mul_f32_e32 v165, v126, v104
	v_fma_f32 v164, v127, v137, v164
	v_fma_f32 v165, v127, v105, v165
	v_fma_f32 v164, v128, v138, v164
	v_fma_f32 v165, v128, v106, v165
	v_fma_f32 v164, v129, v139, v164
	v_fma_f32 v165, v129, v107, v165
	s_waitcnt lgkmcnt(14)
	v_fma_f32 v160, v126, v140, v160
	v_add_f32_dpp v164, v164, v164 quad_perm:[1,0,3,2] row_mask:0xf bank_mask:0xf bound_ctrl:1
	v_fma_f32 v161, v127, v141, v161
	v_add_f32_dpp v165, v165, v165 quad_perm:[1,0,3,2] row_mask:0xf bank_mask:0xf bound_ctrl:1
	v_add_f32_dpp v164, v164, v164 quad_perm:[2,3,0,1] row_mask:0xf bank_mask:0xf bound_ctrl:1
	v_fma_f32 v162, v128, v142, v162
	v_add_f32_dpp v165, v165, v165 quad_perm:[2,3,0,1] row_mask:0xf bank_mask:0xf bound_ctrl:1
	v_add_f32_dpp v164, v164, v164 row_half_mirror row_mask:0xf bank_mask:0xf bound_ctrl:1
	v_fma_f32 v163, v129, v143, v163
	v_add_f32_dpp v165, v165, v165 row_half_mirror row_mask:0xf bank_mask:0xf bound_ctrl:1
	v_add_f32_dpp v164, v164, v164 row_mirror row_mask:0xf bank_mask:0xf bound_ctrl:1
	s_waitcnt lgkmcnt(10)
	v_mul_f32_e32 v156, v60, v40
	v_add_f32_dpp v165, v165, v165 row_mirror row_mask:0xf bank_mask:0xf bound_ctrl:1
	v_fma_f32 v126, v164, v144, v160
	v_cndmask_b32_e64 v11, v11, v165, s[10:11]
	s_lshl_b64 s[10:11], s[10:11], 1
	v_fma_f32 v127, v164, v145, v161
	v_mul_f32_e32 v157, v60, v41
	v_fma_f32 v128, v164, v146, v162
	v_mul_f32_e32 v158, v60, v42
	v_fma_f32 v129, v164, v147, v163
	v_mul_f32_e32 v159, v60, v43
	s_waitcnt lgkmcnt(9)
	ds_read_b128 v[88:91], v219 offset:22016
	ds_read_b32 v108, v218 offset:22784
	ds_read_b128 v[92:95], v219 offset:22272
	ds_read_b128 v[96:99], v219 offset:21760
	ds_read_b128 v[100:103], v219 offset:22528
	ds_read_b128 v[104:107], v219 offset:21504
	v_mul_f32_e32 v164, v126, v44
	v_mul_f32_e32 v165, v126, v148
	v_fma_f32 v164, v127, v45, v164
	v_fma_f32 v165, v127, v149, v165
	v_fma_f32 v164, v128, v46, v164
	v_fma_f32 v165, v128, v150, v165
	v_fma_f32 v164, v129, v47, v164
	v_fma_f32 v165, v129, v151, v165
	s_waitcnt lgkmcnt(14)
; DI unsigned short f2bf(float x) { return (unsigned short)(pack2(x, 0.f) & 0xffffu); }
; DI void phase_scan(const Params& P, int l, char* smem) {
;     ...
;       {
;         float4 Ar[4], Aw[4], Ak[4], Aa[4], Ab[4], Br[4], Bw[4], Bk[4], Ba[4], Bb[4];
;         float Av[4], Bv[4];
;         SCAN_LOAD(A, 0);
;         SCAN_LOAD(B, 1);
;         SCAN_STEPS(A, 0);
;         SCAN_LOAD(A, 2);
;         SCAN_STEPS(B, 1);
;         SCAN_LOAD(B, 3);
;         SCAN_STEPS(A, 2);
;         SCAN_STEPS(B, 3);
;       }
;     ...
;       {
;         int i = c * 16 + kl;
;         int s = dir == 0 ? i : (i < 256 ? 255 - i : 16895 - i);
;         Y[((size_t)b * SB + s) * 1024 + st] = f2bf(ykeep);
;       }
	v_fma_f32 v156, v126, v48, v156
	v_add_f32_dpp v164, v164, v164 quad_perm:[1,0,3,2] row_mask:0xf bank_mask:0xf bound_ctrl:1
	v_fma_f32 v157, v127, v49, v157
	v_add_f32_dpp v165, v165, v165 quad_perm:[1,0,3,2] row_mask:0xf bank_mask:0xf bound_ctrl:1
	v_add_f32_dpp v164, v164, v164 quad_perm:[2,3,0,1] row_mask:0xf bank_mask:0xf bound_ctrl:1
	v_fma_f32 v158, v128, v50, v158
	v_add_f32_dpp v165, v165, v165 quad_perm:[2,3,0,1] row_mask:0xf bank_mask:0xf bound_ctrl:1
	v_add_f32_dpp v164, v164, v164 row_half_mirror row_mask:0xf bank_mask:0xf bound_ctrl:1
	v_fma_f32 v159, v129, v51, v159
	v_add_f32_dpp v165, v165, v165 row_half_mirror row_mask:0xf bank_mask:0xf bound_ctrl:1
	v_add_f32_dpp v164, v164, v164 row_mirror row_mask:0xf bank_mask:0xf bound_ctrl:1
	s_waitcnt lgkmcnt(10)
	v_mul_f32_e32 v160, v84, v64
	v_add_f32_dpp v165, v165, v165 row_mirror row_mask:0xf bank_mask:0xf bound_ctrl:1
	v_fma_f32 v126, v164, v52, v156
	v_cndmask_b32_e64 v11, v11, v165, s[10:11]
	s_lshl_b64 s[10:11], s[10:11], 1
	v_fma_f32 v127, v164, v53, v157
	v_mul_f32_e32 v161, v84, v65
	v_fma_f32 v128, v164, v54, v158
	v_mul_f32_e32 v162, v84, v66
	v_fma_f32 v129, v164, v55, v159
	v_mul_f32_e32 v163, v84, v67
	s_waitcnt lgkmcnt(9)
	ds_read_b128 v[132:135], v219 offset:23552
	ds_read_b32 v152, v218 offset:24320
	ds_read_b128 v[136:139], v219 offset:23808
	ds_read_b128 v[140:143], v219 offset:23296
	ds_read_b128 v[144:147], v219 offset:24064
	ds_read_b128 v[148:151], v219 offset:23040
	v_mul_f32_e32 v164, v126, v68
	v_mul_f32_e32 v165, v126, v56
	v_fma_f32 v164, v127, v69, v164
	v_fma_f32 v165, v127, v57, v165
	v_fma_f32 v164, v128, v70, v164
	v_fma_f32 v165, v128, v58, v165
	v_fma_f32 v164, v129, v71, v164
	v_fma_f32 v165, v129, v59, v165
	s_waitcnt lgkmcnt(14)
	v_fma_f32 v160, v126, v72, v160
	v_add_f32_dpp v164, v164, v164 quad_perm:[1,0,3,2] row_mask:0xf bank_mask:0xf bound_ctrl:1
	v_fma_f32 v161, v127, v73, v161
	v_add_f32_dpp v165, v165, v165 quad_perm:[1,0,3,2] row_mask:0xf bank_mask:0xf bound_ctrl:1
	v_add_f32_dpp v164, v164, v164 quad_perm:[2,3,0,1] row_mask:0xf bank_mask:0xf bound_ctrl:1
	v_fma_f32 v162, v128, v74, v162
	v_add_f32_dpp v165, v165, v165 quad_perm:[2,3,0,1] row_mask:0xf bank_mask:0xf bound_ctrl:1
	v_add_f32_dpp v164, v164, v164 row_half_mirror row_mask:0xf bank_mask:0xf bound_ctrl:1
	v_fma_f32 v163, v129, v75, v163
	v_add_f32_dpp v165, v165, v165 row_half_mirror row_mask:0xf bank_mask:0xf bound_ctrl:1
	v_add_f32_dpp v164, v164, v164 row_mirror row_mask:0xf bank_mask:0xf bound_ctrl:1
	s_waitcnt lgkmcnt(10)
	v_mul_f32_e32 v156, v108, v88
	v_add_f32_dpp v165, v165, v165 row_mirror row_mask:0xf bank_mask:0xf bound_ctrl:1
	v_fma_f32 v126, v164, v76, v160
	v_cndmask_b32_e64 v11, v11, v165, s[10:11]
	s_lshl_b64 s[10:11], s[10:11], 1
	v_fma_f32 v127, v164, v77, v161
	v_mul_f32_e32 v157, v108, v89
	v_fma_f32 v128, v164, v78, v162
	v_mul_f32_e32 v158, v108, v90
	v_fma_f32 v129, v164, v79, v163
	v_mul_f32_e32 v159, v108, v91
	s_waitcnt lgkmcnt(9)
	v_mul_f32_e32 v164, v126, v92
	v_mul_f32_e32 v165, v126, v80
	v_fma_f32 v164, v127, v93, v164
	v_fma_f32 v165, v127, v81, v165
	v_fma_f32 v164, v128, v94, v164
	v_fma_f32 v165, v128, v82, v165
	v_fma_f32 v164, v129, v95, v164
	v_fma_f32 v165, v129, v83, v165
	s_waitcnt lgkmcnt(8)
	v_fma_f32 v156, v126, v96, v156
	v_add_f32_dpp v164, v164, v164 quad_perm:[1,0,3,2] row_mask:0xf bank_mask:0xf bound_ctrl:1
	v_fma_f32 v157, v127, v97, v157
	v_add_f32_dpp v165, v165, v165 quad_perm:[1,0,3,2] row_mask:0xf bank_mask:0xf bound_ctrl:1
	v_add_f32_dpp v164, v164, v164 quad_perm:[2,3,0,1] row_mask:0xf bank_mask:0xf bound_ctrl:1
	v_fma_f32 v158, v128, v98, v158
	v_add_f32_dpp v165, v165, v165 quad_perm:[2,3,0,1] row_mask:0xf bank_mask:0xf bound_ctrl:1
	v_add_f32_dpp v164, v164, v164 row_half_mirror row_mask:0xf bank_mask:0xf bound_ctrl:1
	v_fma_f32 v159, v129, v99, v159
	v_add_f32_dpp v165, v165, v165 row_half_mirror row_mask:0xf bank_mask:0xf bound_ctrl:1
	v_add_f32_dpp v164, v164, v164 row_mirror row_mask:0xf bank_mask:0xf bound_ctrl:1
	s_waitcnt lgkmcnt(4)
	v_mul_f32_e32 v160, v152, v132
	v_add_f32_dpp v165, v165, v165 row_mirror row_mask:0xf bank_mask:0xf bound_ctrl:1
	v_fma_f32 v126, v164, v100, v156
	v_cndmask_b32_e64 v11, v11, v165, s[10:11]
	s_lshl_b64 s[10:11], s[10:11], 1
	v_fma_f32 v127, v164, v101, v157
	v_mul_f32_e32 v161, v152, v133
	v_fma_f32 v128, v164, v102, v158
	v_mul_f32_e32 v162, v152, v134
	v_fma_f32 v129, v164, v103, v159
	v_mul_f32_e32 v163, v152, v135
	s_waitcnt lgkmcnt(3)
	v_mul_f32_e32 v164, v126, v136
	v_mul_f32_e32 v165, v126, v104
	v_fma_f32 v164, v127, v137, v164
	v_fma_f32 v165, v127, v105, v165
	v_fma_f32 v164, v128, v138, v164
	v_fma_f32 v165, v128, v106, v165
	v_fma_f32 v164, v129, v139, v164
	v_fma_f32 v165, v129, v107, v165
	s_waitcnt lgkmcnt(2)
	v_fma_f32 v160, v126, v140, v160
	v_add_f32_dpp v164, v164, v164 quad_perm:[1,0,3,2] row_mask:0xf bank_mask:0xf bound_ctrl:1
	v_fma_f32 v161, v127, v141, v161
	v_add_f32_dpp v165, v165, v165 quad_perm:[1,0,3,2] row_mask:0xf bank_mask:0xf bound_ctrl:1
	v_add_f32_dpp v164, v164, v164 quad_perm:[2,3,0,1] row_mask:0xf bank_mask:0xf bound_ctrl:1
	v_fma_f32 v162, v128, v142, v162
	v_add_f32_dpp v165, v165, v165 quad_perm:[2,3,0,1] row_mask:0xf bank_mask:0xf bound_ctrl:1
	v_add_f32_dpp v164, v164, v164 row_half_mirror row_mask:0xf bank_mask:0xf bound_ctrl:1
	v_fma_f32 v163, v129, v143, v163
	v_add_f32_dpp v165, v165, v165 row_half_mirror row_mask:0xf bank_mask:0xf bound_ctrl:1
	v_add_f32_dpp v164, v164, v164 row_mirror row_mask:0xf bank_mask:0xf bound_ctrl:1
	s_nop 0
	v_add_f32_dpp v165, v165, v165 row_mirror row_mask:0xf bank_mask:0xf bound_ctrl:1
	s_waitcnt lgkmcnt(1)
	v_fma_f32 v126, v164, v144, v160
	v_cndmask_b32_e64 v11, v11, v165, s[10:11]
	s_lshl_b64 s[10:11], s[10:11], 1
	v_fma_f32 v127, v164, v145, v161
	v_fma_f32 v128, v164, v146, v162
	v_fma_f32 v129, v164, v147, v163
	s_waitcnt lgkmcnt(0)
	v_mul_f32_e32 v165, v126, v148
	v_fma_f32 v165, v127, v149, v165
	v_fma_f32 v165, v128, v150, v165
	v_fma_f32 v165, v129, v151, v165
	s_nop 1
	v_add_f32_dpp v165, v165, v165 quad_perm:[1,0,3,2] row_mask:0xf bank_mask:0xf bound_ctrl:1
	s_nop 1
	v_add_f32_dpp v165, v165, v165 quad_perm:[2,3,0,1] row_mask:0xf bank_mask:0xf bound_ctrl:1
	s_nop 1
	v_add_f32_dpp v165, v165, v165 row_half_mirror row_mask:0xf bank_mask:0xf bound_ctrl:1
	s_nop 1
	v_add_f32_dpp v165, v165, v165 row_mirror row_mask:0xf bank_mask:0xf bound_ctrl:1
	v_cndmask_b32_e64 v11, v11, v165, s[10:11]
	v_add_u32_e32 v10, s9, v216
	v_cndmask_b32_e64 v10, v10, v217, s[4:5]
	v_cvt_pk_bf16_f32 v12, v11, s0
	v_ashrrev_i32_e32 v11, 31, v10
	v_lshl_add_u64 v[10:11], s[6:7], 0, v[10:11]
	v_lshlrev_b64 v[10:11], 11, v[10:11]
	v_lshl_add_u64 v[10:11], v[188:189], 0, v[10:11]
	global_store_short v[10:11], v12, off
	s_cbranch_vccnz .LBB0_510
; DI float bflo(unsigned u) { return __uint_as_float(u << 16); }
; DI float bfhi(unsigned u) { return __uint_as_float(u & 0xffff0000u); }
; DI void vm_wait5x2(u32x2& a, u32x2& b, u32x2& c, u32x2& d, u32x2& e) { cfence(); }
; DI float fma_(float a, float b, float c) { float d; asm("v_fma_f32 %0, %1, %2, %3" : "=v"(d) : "v"(a), "v"(b), "v"(c)); return d; }
; DI float mul_(float a, float b) { float d; asm("v_mul_f32 %0, %1, %2" : "=v"(d) : "v"(a), "v"(b)); return d; }
; DI float add_(float a, float b) { float d; asm("v_add_f32 %0, %1, %2" : "=v"(d) : "v"(a), "v"(b)); return d; }
; DI float fma_n_(float a, float b, float c) { float d; asm("v_fma_f32 %0, %1, %2, %3\n\ts_nop 1" : "=v"(d) : "v"(a), "v"(b), "v"(c)); return d; }
; DI void scan_prep(u32x2 (&raw)[5], const float (&kkw)[4], const float (&kaw)[4], float* dst  ) {
;   vm_wait5x2(raw[0], raw[1], raw[2], raw[3], raw[4]);
;   float r[4] = {bflo(raw[0].x), bfhi(raw[0].x), bflo(raw[0].y), bfhi(raw[0].y)};
;   float k[4] = {bflo(raw[1].x), bfhi(raw[1].x), bflo(raw[1].y), bfhi(raw[1].y)};
;   float v[4] = {bflo(raw[2].x), bfhi(raw[2].x), bflo(raw[2].y), bfhi(raw[2].y)};
;   float e[4] = {bflo(raw[3].x), bfhi(raw[3].x), bflo(raw[3].y), bfhi(raw[3].y)};
;   float a[4] = {bflo(raw[4].x), bfhi(raw[4].x), bflo(raw[4].y), bfhi(raw[4].y)};
;   float kr[4], ss = 0.f;
; #pragma unroll
;   for (int i = 0; i < 4; ++i) { kr[i] = mul_(k[i], kkw[i]); ss = (i < 3) ? fma_(kr[i], kr[i], ss) : fma_n_(kr[i], kr[i], ss); }
;   ss = reduce16(ss);
;   const float inv = __builtin_amdgcn_rcpf(fmaxf(__builtin_amdgcn_sqrtf(ss), 1e-12f));
;   float w4[4], kd4[4], a4[4], b4[4];
; #pragma unroll
;   for (int i = 0; i < 4; ++i) {
;     float kn = kr[i] * inv;
;     w4[i] = __builtin_amdgcn_exp2f(mul_(e[i], -LOG2E));
;     kd4[i] = mul_(k[i], fma_(add_(a[i], -1.f), kaw[i], 1.f));
;     a4[i] = -kn;
;     b4[i] = mul_(kn, a[i]);
;   }
;   *(float4*)(dst) = float4{r[0], r[1], r[2], r[3]};
;   *(float4*)(dst + 64) = float4{w4[0], w4[1], w4[2], w4[3]};
;   *(float4*)(dst + 128) = float4{kd4[0], kd4[1], kd4[2], kd4[3]};
;   *(float4*)(dst + 192) = float4{a4[0], a4[1], a4[2], a4[3]};
;   *(float4*)(dst + 256) = float4{b4[0], b4[1], b4[2], b4[3]};
;   *(float4*)(dst + 320) = float4{v[0], v[1], v[2], v[3]};
	s_waitcnt vmcnt(4)
	v_lshlrev_b32_e32 v11, 16, v176
	v_mul_f32 v12, v11, v2
	v_and_b32_e32 v15, 0xffff0000, v176
	v_fma_f32 v10, v12, v12, v1
	v_mul_f32 v13, v15, v3
	v_lshlrev_b32_e32 v16, 16, v177
	v_fma_f32 v10, v13, v13, v10
	v_mul_f32 v28, v16, v4
	v_and_b32_e32 v17, 0xffff0000, v177
	v_fma_f32 v10, v28, v28, v10
	v_mul_f32 v29, v17, v5
	s_waitcnt vmcnt(2)
	v_lshlrev_b32_e32 v14, 16, v178
	v_fma_f32 v10, v29, v29, v10
	s_nop 1
	s_waitcnt vmcnt(1)
	v_lshlrev_b32_e32 v26, 16, v182
	v_lshlrev_b32_e32 v33, 16, v179
	v_add_f32_dpp v10, v10, v10 quad_perm:[1,0,3,2] row_mask:0xf bank_mask:0xf bound_ctrl:1
	v_and_b32_e32 v27, 0xffff0000, v182
	v_and_b32_e32 v30, 0xffff0000, v178
	v_add_f32_dpp v10, v10, v10 quad_perm:[2,3,0,1] row_mask:0xf bank_mask:0xf bound_ctrl:1
	v_lshlrev_b32_e32 v35, 16, v183
	v_and_b32_e32 v37, 0xffff0000, v179
	v_add_f32_dpp v10, v10, v10 row_half_mirror row_mask:0xf bank_mask:0xf bound_ctrl:1
	s_bitcmp1_b32 s8, 0
	s_cselect_b32 s9, 0x6000, 0
	v_add_f32_dpp v10, v10, v10 row_mirror row_mask:0xf bank_mask:0xf bound_ctrl:1
	v_sqrt_f32_e32 v10, v10
	v_add_u32_e32 v34, s9, v192
	v_and_b32_e32 v36, 0xffff0000, v183
	v_and_b32_e32 v25, 0xffff0000, v175
	v_max_f32_e32 v10, 0x2b8cbccc, v10
	v_rcp_f32_e32 v32, v10
	v_mul_f32 v10, v14, v196
	v_add_f32 v14, v26, v197
	v_lshlrev_b32_e32 v24, 16, v175
	v_fma_f32 v14, v14, v6, v198
	v_pk_mul_f32 v[12:13], v[12:13], v[32:33] op_sel_hi:[1,0]
	v_mul_f32 v14, v11, v14
	v_mul_f32 v11, v30, v196
	v_add_f32 v30, v27, v197
	v_exp_f32_e32 v10, v10
	v_xor_b32_e32 v31, 0x80000000, v13
	v_mul_f32 v27, v13, v27
	v_add_f32 v13, v35, v197
	v_fma_f32 v30, v30, v7, v198
	v_mul_f32 v26, v12, v26
	v_exp_f32_e32 v11, v11
	v_fma_f32 v13, v13, v8, v198
	v_mul_f32 v15, v15, v30
	v_xor_b32_e32 v30, 0x80000000, v12
	v_mul_f32 v12, v33, v196
	v_mul_f32 v16, v16, v13
	v_mul_f32 v13, v37, v196
	v_pk_mul_f32 v[28:29], v[28:29], v[32:33] op_sel_hi:[1,0]
	v_exp_f32_e32 v12, v12
	v_exp_f32_e32 v13, v13
	v_and_b32_e32 v23, 0xffff0000, v174
	v_lshlrev_b32_e32 v22, 16, v174
	v_xor_b32_e32 v32, 0x80000000, v28
	v_mul_f32 v28, v28, v35
	v_add_f32 v35, v36, v197
	v_and_b32_e32 v21, 0xffff0000, v181
	v_lshlrev_b32_e32 v20, 16, v181
	v_and_b32_e32 v19, 0xffff0000, v180
	v_lshlrev_b32_e32 v18, 16, v180
	v_xor_b32_e32 v33, 0x80000000, v29
	v_fma_f32 v35, v35, v9, v198
	v_mul_f32 v29, v29, v36
	s_nop 0
	v_mul_f32 v17, v17, v35
	ds_write_b128 v34, v[22:25]
	ds_write_b128 v34, v[10:13] offset:256
	ds_write_b128 v34, v[14:17] offset:512
	ds_write_b128 v34, v[30:33] offset:768
	ds_write_b128 v34, v[26:29] offset:1024
	ds_write_b128 v34, v[18:21] offset:1280
	s_branch .LBB0_510

; __global__ void __launch_bounds__(256, 2) mega(Params P) {
;     ...
;   const int p0 = P.p0, p1 = P.p1;
;   for (int ph = p0; ph < p1; ++ph) {
;     if (phase_empty(ph)) continue;
;     const __attribute__((address_space(4))) char* kp = (const __attribute__((address_space(4))) char*)__builtin_amdgcn_kernarg_segment_ptr();
;     asm volatile("" : "+s"(kp));
;     const Params& Pr = *(const Params*)(kp);
;     int nrep = 1;
;     ...
;     if (ph >= 2 && ph < 32 && ((REP_MASK >> ((ph - 2) % 15)) & 1)) nrep = 2;
;     ...
; #pragma unroll 1
;     for (int rep = 0; rep < nrep; ++rep) run_phase(Pr, ph, smem);
;     if (ph + 1 < p1) cg::this_grid().sync();
;   }
.LBB0_785:
	s_add_i32 s8, s28, 1
	s_cmp_ge_i32 s8, s29
	s_cbranch_scc1 .LBB0_4
	s_waitcnt vmcnt(0) lgkmcnt(0)
	s_barrier
	s_mov_b64 s[0:1], exec
	v_readlane_b32 s2, v253, 1
	v_readlane_b32 s3, v253, 2
	s_and_b64 s[2:3], s[0:1], s[2:3]
	s_mov_b64 exec, s[2:3]
	s_cbranch_execz .LBB0_3
	s_load_dwordx2 s[2:3], s[30:31], 0x58
	s_add_u32 s4, s30, 0xfffffff0
	s_addc_u32 s5, s31, -1
	s_load_dwordx2 s[4:5], s[4:5], 0x0
	s_waitcnt lgkmcnt(0)
	s_add_u32 s4, s4, 0x5bd0000
	s_addc_u32 s5, s5, 0
	s_cmp_lg_u32 s28, 0
	s_cbranch_scc1 .Lgs_use_ws
	v_readlane_b32 s6, v253, 0
	s_nop 3
	s_cmp_lg_u32 s6, 0
	s_cbranch_scc1 .Lgs_go
	global_load_dword v0, v1, s[2:3] offset:40
	v_mov_b32_e32 v2, 0
	s_waitcnt vmcnt(0)
	global_store_dword v1, v2, s[4:5] offset:32 sc0 sc1
	global_store_dword v1, v0, s[4:5] offset:40 sc0 sc1
	s_waitcnt vmcnt(0)
	s_branch .Lgs_go
.Lgs_use_ws:
	s_mov_b64 s[2:3], s[4:5]
.Lgs_go:
	buffer_wbl2 sc1
	s_waitcnt vmcnt(0)
	s_mov_b64 s[4:5], exec
	v_mbcnt_lo_u32_b32 v2, s4, 0
	v_mbcnt_hi_u32_b32 v2, s5, v2
	v_cmp_eq_u32_e32 vcc, 0, v2
	global_load_dword v0, v1, s[2:3] offset:40 sc1
	s_and_saveexec_b64 s[6:7], vcc
	s_cbranch_execz .LBB0_789
	s_bcnt1_i32_b64 s4, s[4:5]
	v_mov_b32_e32 v3, s4
	global_atomic_add v3, v1, v3, s[2:3] offset:32 sc0
